# attention: next-tile K/V address calc and loads spread over the first 8 QK MFMA gaps (placed after the fragment reads)
# speedup vs baseline: 1.1475x; 1.0062x over previous
; template <bool SAMPLE>
; DEV void attn_unit(CParams& p, int layer, int unit, float lam, float lam_init, char* lds, const int swave) {
;     ...
;   for (int t = 0; t < ntiles; ++t) {
;     const int tn = SAMPLE ? t + 1 : (t + 1 < ntiles ? t + 1 : t);
;     if (!SAMPLE || t + 1 < ntiles) gloadK(tn);
;     if (t < my_tiles) {
;       const char* Ks = lds + (t & 1) * A_BUF; const char* Vs = Ks + A_KT;
;       bf16x8 pf[2][4];
;       f32x16 S0, S1;
;       auto qk = [&](int br) {
;         const f32x16 zc = {0.f, 0.f, 0.f, 0.f, 0.f, 0.f, 0.f, 0.f, 0.f, 0.f, 0.f, 0.f, 0.f, 0.f, 0.f, 0.f};
; #pragma unroll
;         for (int ks = 0; ks < 4; ++ks) {
;           const bf16x8 k0 = lds_read8(Ks + lr * AK_B + (br * 64 + ks * 16 + hh * 8) * 2);
;           const bf16x8 k1 = lds_read8(Ks + (32 + lr) * AK_B + (br * 64 + ks * 16 + hh * 8) * 2);
;           S0 = mfma32(k0, qf[br][ks], ks == 0 ? zc : S0); S1 = mfma32(k1, qf[br][ks], ks == 0 ? zc : S1);
;         }
;         if (sample && t == 32) {
; #pragma unroll
;           for (int r = 0; r < 16; ++r) { if (r >= 8) S0[r] = -1e30f; S1[r] = -1e30f; }
;         }
;       };
;       auto sm8 = [&](const f32x16& Sx, int r0, float nm, float& lsum) -> bf16x8 {
;         f32x2 c2; c2[0] = cexp; c2[1] = cexp;
;         f32x2 nm2; nm2[0] = nm; nm2[1] = nm;
;         union { u32x4 u; bf16x8 b; } x;
;         f32x2 sum2; sum2[0] = 0.f; sum2[1] = 0.f;
; #pragma unroll
;         for (int r = 0; r < 8; r += 2) {
;           f32x2 v; v[0] = Sx[r0 + r]; v[1] = Sx[r0 + r + 1];
;           v = v * c2 + nm2;
;           f32x2 ex; ex[0] = __builtin_amdgcn_exp2f(v[0]); ex[1] = __builtin_amdgcn_exp2f(v[1]);
;           sum2 += ex;
;           x.u[r >> 1] = pk2(ex[0], ex[1]);
;         }
;         lsum += sum2[0] + sum2[1];
;         return x.b;
;       };
;       qk(0);
;       pf[0][0] = sm8(S0, 0, nmc[0], ls[0]); pf[0][1] = sm8(S0, 8, nmc[0], ls[0]);
;       pf[0][2] = sm8(S1, 0, nmc[0], ls[0]); pf[0][3] = sm8(S1, 8, nmc[0], ls[0]);
;       qk(1);
;       if (!SAMPLE || t + 1 < ntiles) gloadV(tn);
; #pragma unroll
;       for (int sl = 0; sl < 4; ++sl) {
; #pragma unroll
;         for (int e = 0; e < 4; ++e) {
;           const bf16x8 vf = tr8(Vs, AV_B, sl * 16, e * 32, lane);
;           O1[e] = mfma32(vf, pf[0][sl], O1[e]);
;         }
;         pf[1][sl] = sm8(sl < 2 ? S0 : S1, (sl & 1) * 8, nmc[1], ls[1]);
.LBB0_243:
	s_add_i32 s36, s37, 1
	s_cmp_ge_u32 s36, s23
	s_cselect_b64 s[6:7], -1, 0
	s_cmp_lt_u32 s36, s23
	s_cselect_b32 s100, s36, s37
	s_lshl_b32 s101, s100, 6
	s_cmp_ge_u32 s37, s29
	s_cbranch_scc1 .LBB0_245
	s_bitcmp1_b32 s37, 0
	s_cselect_b32 s38, 0x9400, 0
	s_add_i32 s38, s38, 16
	v_add_u32_e32 v118, s38, v243
	ds_read_b128 v[62:65], v118
	ds_read_b128 v[66:69], v118 offset:32
	s_waitcnt lgkmcnt(1)
	v_mfma_f32_32x32x16_bf16 v[178:193], v[62:65], v[16:19], 0
	ds_read_b128 v[62:65], v118 offset:8704
	ds_read_b128 v[70:73], v118 offset:8736
	s_add_i32 s8, s101, s28
	s_mul_hi_i32 s9, s8, 0xc00
	s_mulk_i32 s8, 0xc00
	s_or_b64 s[8:9], s[8:9], s[2:3]
	s_waitcnt lgkmcnt(1)
	v_mfma_f32_32x32x16_bf16 v[210:225], v[62:65], v[16:19], 0
	v_lshl_add_u64 v[54:55], s[8:9], 1, v[50:51]
	global_load_dwordx4 a[160:163], v[54:55], off
	global_load_dwordx4 a[144:147], v[54:55], off offset:1024
	v_mfma_f32_32x32x16_bf16 v[178:193], v[66:69], v[20:23], v[178:193]
	ds_read_b128 v[62:65], v118 offset:64
	ds_read_b128 v[66:69], v118 offset:96
	s_add_i32 s8, s30, s101
	s_mul_hi_i32 s9, s8, 0xc00
	s_mulk_i32 s8, 0xc00
	s_or_b64 s[8:9], s[8:9], s[2:3]
	s_waitcnt lgkmcnt(2)
	v_mfma_f32_32x32x16_bf16 v[210:225], v[70:73], v[20:23], v[210:225]
	v_lshl_add_u64 v[56:57], s[8:9], 1, v[50:51]
	global_load_dwordx4 a[164:167], v[56:57], off
	global_load_dwordx4 a[148:151], v[56:57], off offset:1024
	s_waitcnt lgkmcnt(1)
	v_mfma_f32_32x32x16_bf16 v[178:193], v[62:65], v[24:27], v[178:193]
	ds_read_b128 v[62:65], v118 offset:8768
	ds_read_b128 v[70:73], v118 offset:8800
	ds_read_b128 v[88:91], v118 offset:128
	s_add_i32 s8, s31, s101
	s_mul_hi_i32 s9, s8, 0xc00
	s_mulk_i32 s8, 0xc00
	s_or_b64 s[8:9], s[8:9], s[2:3]
	s_waitcnt lgkmcnt(2)
	v_mfma_f32_32x32x16_bf16 v[210:225], v[62:65], v[24:27], v[210:225]
	v_lshl_add_u64 v[58:59], s[8:9], 1, v[50:51]
	global_load_dwordx4 a[168:171], v[58:59], off
	global_load_dwordx4 a[152:155], v[58:59], off offset:1024
	s_waitcnt lgkmcnt(0)
	v_mfma_f32_32x32x16_bf16 v[226:241], v[88:91], v[32:35], 0
	s_add_i32 s8, s34, s101
	s_mul_hi_i32 s9, s8, 0xc00
	s_mulk_i32 s8, 0xc00
	s_or_b64 s[8:9], s[8:9], s[2:3]
	v_mfma_f32_32x32x16_bf16 v[178:193], v[66:69], v[28:31], v[178:193]
	v_lshl_add_u64 v[60:61], s[8:9], 1, v[50:51]
	global_load_dwordx4 a[172:175], v[60:61], off
	global_load_dwordx4 a[156:159], v[60:61], off offset:1024
	s_nop 11
	v_fma_f32 v102, v180, s52, v48
	v_fma_f32 v103, v181, s52, v49
	v_fma_f32 v62, v184, s52, v48
	v_fma_f32 v63, v185, s52, v49
	v_fma_f32 v66, v190, s52, v48
	v_fma_f32 v67, v191, s52, v49
	v_mfma_f32_32x32x16_bf16 v[210:225], v[70:73], v[28:31], v[210:225]
	ds_read_b128 v[68:71], v118 offset:8832
	ds_read_b128 v[92:95], v118 offset:160
	ds_read_b128 v[88:91], v118 offset:8864
	s_waitcnt lgkmcnt(2)
	v_exp_f32_e32 v66, v66
	v_mfma_f32_32x32x16_bf16 v[194:209], v[68:71], v[32:35], 0
	s_waitcnt lgkmcnt(1)
	v_exp_f32_e32 v67, v67
	v_fma_f32 v64, v192, s52, v48
	v_fma_f32 v65, v193, s52, v49
	s_nop 1
	v_fma_f32 v74, v218, s52, v48
	v_mfma_f32_32x32x16_bf16 v[226:241], v[92:95], v[36:39], v[226:241]
	ds_read_b128 v[92:95], v118 offset:192
	s_waitcnt lgkmcnt(1)
	v_fma_f32 v75, v219, s52, v49
	v_fma_f32 v72, v220, s52, v48
	v_fma_f32 v73, v221, s52, v49
	v_exp_f32_e32 v74, v74
	v_mfma_f32_32x32x16_bf16 v[194:209], v[88:91], v[36:39], v[194:209]
	v_fma_f32 v88, v178, s52, v48
	v_fma_f32 v89, v179, s52, v49
	v_exp_f32_e32 v100, v88
	v_exp_f32_e32 v101, v89
	ds_read_b128 v[88:91], v118 offset:8896
	ds_read_b128 v[96:99], v118 offset:224
	s_waitcnt lgkmcnt(2)
	v_mfma_f32_32x32x16_bf16 v[226:241], v[92:95], v[40:43], v[226:241]
	v_exp_f32_e32 v94, v102
	v_exp_f32_e32 v95, v103
	v_cvt_pk_bf16_f32 v92, v100, v101
	v_add_f32_e32 v116, v94, v100
	v_add_f32_e32 v117, v95, v101
	ds_read_b128 v[100:103], v118 offset:8928
	s_waitcnt lgkmcnt(2)
	v_mfma_f32_32x32x16_bf16 v[194:209], v[88:91], v[40:43], v[194:209]
	v_add3_u32 v108, s38, v87, v86
	v_fma_f32 v88, v182, s52, v48
	v_fma_f32 v89, v183, s52, v49
	v_exp_f32_e32 v90, v62
	v_exp_f32_e32 v88, v88
	v_exp_f32_e32 v89, v89
	v_exp_f32_e32 v91, v63
	v_add_f32_e32 v62, v88, v116
	v_add_f32_e32 v63, v89, v117
	ds_read_b64_tr_b16 v[116:117], v108 offset:17408
	ds_read_b64_tr_b16 v[118:119], v108 offset:19968
	s_waitcnt lgkmcnt(2)
	v_mfma_f32_32x32x16_bf16 v[194:209], v[100:103], v[44:47], v[194:209]
	ds_read_b64_tr_b16 v[100:101], v108 offset:17472
	ds_read_b64_tr_b16 v[122:123], v108 offset:17536
	ds_read_b64_tr_b16 v[142:143], v108 offset:17600
	ds_read_b64_tr_b16 v[102:103], v108 offset:20032
	ds_read_b64_tr_b16 v[124:125], v108 offset:20096
	ds_read_b64_tr_b16 v[144:145], v108 offset:20160
	v_mfma_f32_32x32x16_bf16 v[226:241], v[96:99], v[44:47], v[226:241]
	s_waitcnt lgkmcnt(6)
	v_cvt_pk_bf16_f32 v93, v94, v95
	v_cvt_pk_bf16_f32 v94, v88, v89
	v_cvt_pk_bf16_f32 v95, v90, v91
	v_fma_f32 v88, v186, s52, v48
	v_fma_f32 v89, v187, s52, v49
	v_mfma_f32_32x32x16_bf16 a[0:15], v[116:119], v[92:95], a[0:15]
	ds_read_b64_tr_b16 v[146:147], v108 offset:22528
	ds_read_b64_tr_b16 v[148:149], v108 offset:25088
	s_waitcnt lgkmcnt(4)
	v_add_f32_e32 v62, v90, v62
	v_add_f32_e32 v63, v91, v63
	v_exp_f32_e32 v88, v88
	v_mfma_f32_32x32x16_bf16 a[32:47], v[100:103], v[92:95], a[32:47]
	ds_read_b64_tr_b16 v[150:151], v108 offset:22592
	ds_read_b64_tr_b16 v[154:155], v108 offset:22656
	ds_read_b64_tr_b16 v[158:159], v108 offset:22720
	ds_read_b64_tr_b16 v[152:153], v108 offset:25152
	ds_read_b64_tr_b16 v[156:157], v108 offset:25216
	ds_read_b64_tr_b16 v[160:161], v108 offset:25280
	s_waitcnt lgkmcnt(9)
	v_mfma_f32_32x32x16_bf16 a[64:79], v[122:125], v[92:95], a[64:79]
	s_waitcnt lgkmcnt(8)
; DEV uint32_t pk2(float lo, float hi) { f32x2 v; v[0] = lo; v[1] = hi; bf16v2 b = __builtin_convertvector(v, bf16v2); return __builtin_bit_cast(uint32_t, b); }
; DEV f32x16 mfma32(bf16x8 a, bf16x8 b, f32x16 c) { return __builtin_amdgcn_mfma_f32_32x32x16_bf16(a, b, c, 0, 0, 0); }
; template <bool SAMPLE>
; DEV void attn_unit(CParams& p, int layer, int unit, float lam, float lam_init, char* lds, const int swave) {
;     ...
;       auto sm8 = [&](const f32x16& Sx, int r0, float nm, float& lsum) -> bf16x8 {
;         f32x2 c2; c2[0] = cexp; c2[1] = cexp;
;         f32x2 nm2; nm2[0] = nm; nm2[1] = nm;
;         union { u32x4 u; bf16x8 b; } x;
;         f32x2 sum2; sum2[0] = 0.f; sum2[1] = 0.f;
; #pragma unroll
;         for (int r = 0; r < 8; r += 2) {
;           f32x2 v; v[0] = Sx[r0 + r]; v[1] = Sx[r0 + r + 1];
;           v = v * c2 + nm2;
;           f32x2 ex; ex[0] = __builtin_amdgcn_exp2f(v[0]); ex[1] = __builtin_amdgcn_exp2f(v[1]);
;           sum2 += ex;
;           x.u[r >> 1] = pk2(ex[0], ex[1]);
;         }
;         lsum += sum2[0] + sum2[1];
;         return x.b;
;       };
;       qk(0);
;       pf[0][0] = sm8(S0, 0, nmc[0], ls[0]); pf[0][1] = sm8(S0, 8, nmc[0], ls[0]);
;       pf[0][2] = sm8(S1, 0, nmc[0], ls[0]); pf[0][3] = sm8(S1, 8, nmc[0], ls[0]);
;       qk(1);
;       if (!SAMPLE || t + 1 < ntiles) gloadV(tn);
; #pragma unroll
;       for (int sl = 0; sl < 4; ++sl) {
; #pragma unroll
;         for (int e = 0; e < 4; ++e) {
;           const bf16x8 vf = tr8(Vs, AV_B, sl * 16, e * 32, lane);
;           O1[e] = mfma32(vf, pf[0][sl], O1[e]);
;         }
;         pf[1][sl] = sm8(sl < 2 ? S0 : S1, (sl & 1) * 8, nmc[1], ls[1]);
	v_exp_f32_e32 v89, v89
	v_fma_f32 v90, v188, s52, v48
	v_fma_f32 v91, v189, s52, v49
	v_exp_f32_e32 v90, v90
	v_mfma_f32_32x32x16_bf16 a[96:111], v[142:145], v[92:95], a[96:111]
	ds_read_b64_tr_b16 v[162:163], v108 offset:27648
	ds_read_b64_tr_b16 v[164:165], v108 offset:30208
	s_waitcnt lgkmcnt(8)
	v_exp_f32_e32 v91, v91
	v_add_f32_e64 v96, v88, 0
	v_cvt_pk_bf16_f32 v88, v88, v89
	v_add_f32_e32 v96, v90, v96
	v_add_f32_e32 v97, v91, v89
	v_exp_f32_e32 v98, v64
	v_exp_f32_e32 v99, v65
	v_cvt_pk_bf16_f32 v89, v90, v91
	v_cvt_pk_bf16_f32 v90, v66, v67
	v_cvt_pk_bf16_f32 v91, v98, v99
	v_add_f32_e32 v64, v66, v96
	v_add_f32_e32 v65, v67, v97
	v_mfma_f32_32x32x16_bf16 a[0:15], v[146:149], v[88:91], a[0:15]
	ds_read_b64_tr_b16 v[166:167], v108 offset:27712
	ds_read_b64_tr_b16 v[170:171], v108 offset:27776
	ds_read_b64_tr_b16 v[174:175], v108 offset:27840
	ds_read_b64_tr_b16 v[168:169], v108 offset:30272
	ds_read_b64_tr_b16 v[172:173], v108 offset:30336
	ds_read_b64_tr_b16 v[176:177], v108 offset:30400
	s_waitcnt lgkmcnt(10)
	v_mfma_f32_32x32x16_bf16 a[32:47], v[150:153], v[88:91], a[32:47]
	s_waitcnt lgkmcnt(9)
	v_fma_f32 v66, v210, s52, v48
	v_fma_f32 v67, v211, s52, v49
	v_exp_f32_e32 v66, v66
	v_exp_f32_e32 v67, v67
	v_mfma_f32_32x32x16_bf16 a[64:79], v[154:157], v[88:91], a[64:79]
	s_waitcnt lgkmcnt(8)
	v_add_f32_e32 v64, v98, v64
	v_add_f32_e32 v65, v99, v65
	v_fma_f32 v98, v216, s52, v48
	v_fma_f32 v99, v217, s52, v49
	v_fma_f32 v92, v212, s52, v48
	v_mfma_f32_32x32x16_bf16 a[96:111], v[158:161], v[88:91], a[96:111]
	s_waitcnt lgkmcnt(6)
	v_fma_f32 v93, v213, s52, v49
	v_exp_f32_e32 v98, v98
	v_exp_f32_e32 v94, v92
	v_exp_f32_e32 v95, v93
	v_cvt_pk_bf16_f32 v92, v66, v67
	v_exp_f32_e32 v99, v99
	v_add_f32_e64 v66, v94, v66
	v_add_f32_e64 v67, v95, v67
	v_fma_f32 v96, v214, s52, v48
	v_fma_f32 v97, v215, s52, v49
	v_exp_f32_e32 v96, v96
	v_exp_f32_e32 v97, v97
	v_cvt_pk_bf16_f32 v93, v94, v95
	v_cvt_pk_bf16_f32 v94, v96, v97
	v_cvt_pk_bf16_f32 v95, v98, v99
	v_exp_f32_e32 v75, v75
	v_fma_f32 v70, v222, s52, v48
	v_mfma_f32_32x32x16_bf16 a[0:15], v[162:165], v[92:95], a[0:15]
	ds_read_b64_tr_b16 v[178:179], v108 offset:32768
	ds_read_b64_tr_b16 v[180:181], v108 offset:35328
	ds_read_b64_tr_b16 v[182:183], v108 offset:32832
	ds_read_b64_tr_b16 v[186:187], v108 offset:32896
	ds_read_b64_tr_b16 v[190:191], v108 offset:32960
	ds_read_b64_tr_b16 v[184:185], v108 offset:35392
	ds_read_b64_tr_b16 v[188:189], v108 offset:35456
	ds_read_b64_tr_b16 v[192:193], v108 offset:35520
	s_waitcnt lgkmcnt(10)
	v_mfma_f32_32x32x16_bf16 a[32:47], v[166:169], v[92:95], a[32:47]
	s_waitcnt lgkmcnt(9)
	v_fma_f32 v71, v223, s52, v49
	v_exp_f32_e32 v88, v72
	v_exp_f32_e32 v89, v73
	v_mfma_f32_32x32x16_bf16 a[64:79], v[170:173], v[92:95], a[64:79]
	s_waitcnt lgkmcnt(8)
	v_exp_f32_e32 v70, v70
	v_exp_f32_e32 v71, v71
	v_fma_f32 v68, v224, s52, v48
	v_mfma_f32_32x32x16_bf16 a[96:111], v[174:177], v[92:95], a[96:111]
	s_waitcnt lgkmcnt(6)
	v_fma_f32 v69, v225, s52, v49
	v_cvt_pk_bf16_f32 v72, v74, v75
	v_add_f32_e64 v74, v88, v74
	v_add_f32_e64 v75, v89, v75
	v_exp_f32_e32 v90, v68
	v_exp_f32_e32 v91, v69
	v_add_f32_e32 v68, v70, v74
	v_add_f32_e32 v69, v71, v75
	v_cvt_pk_bf16_f32 v74, v70, v71
	v_cvt_pk_bf16_f32 v73, v88, v89
	v_cvt_pk_bf16_f32 v75, v90, v91
	v_add_f32_e32 v66, v96, v66
	v_add_f32_e32 v67, v97, v67
	v_mfma_f32_32x32x16_bf16 a[0:15], v[178:181], v[72:75], a[0:15]
	s_waitcnt lgkmcnt(2)
	v_add_f32_e64 v66, v98, v66
	v_add_f32_e64 v67, v99, v67
	v_fma_f32 v98, v226, s52, v52
	v_fma_f32 v99, v227, s52, v53
	v_fma_f32 v96, v228, s52, v52
	v_mfma_f32_32x32x16_bf16 a[32:47], v[182:185], v[72:75], a[32:47]
	s_waitcnt lgkmcnt(1)
	v_fma_f32 v97, v229, s52, v53
	v_fma_f32 v70, v232, s52, v52
	v_fma_f32 v71, v233, s52, v53
	v_exp_f32_e32 v104, v98
	v_mfma_f32_32x32x16_bf16 a[64:79], v[186:189], v[72:75], a[64:79]
	s_waitcnt lgkmcnt(0)
; DEV f32x16 mfma32(bf16x8 a, bf16x8 b, f32x16 c) { return __builtin_amdgcn_mfma_f32_32x32x16_bf16(a, b, c, 0, 0, 0); }
; template <bool SAMPLE>
; DEV void attn_unit(CParams& p, int layer, int unit, float lam, float lam_init, char* lds, const int swave) {
;     ...
;   auto lwrite = [&](int buf) {
;     char* ks_ = lds + buf * A_BUF; char* vs_ = ks_ + A_KT;
; #pragma unroll
;     for (int i = 0; i < 4; ++i) {
;       const int r = krow + 16 * i;
;       *(u32x4*)(ks_ + r * AK_B + kch * 16) = rk[i];
;       *(u32x4*)(vs_ + r * AV_B + kch * 16) = rv[i];
;     }
;   };
;     ...
; #pragma unroll
;       for (int sl = 0; sl < 4; ++sl)
; #pragma unroll
;         for (int e = 0; e < 4; ++e) {
;           const bf16x8 vf = tr8(Vs, AV_B, sl * 16, e * 32, lane);
;           O2[e] = mfma32(vf, pf[1][sl], O2[e]);
;         }
;     }
;     if (t >= my_tiles && (!SAMPLE || t + 1 < ntiles)) gloadV(tn);
;     if (!SAMPLE || t + 1 < ntiles) lwrite((t + 1) & 1);
;     __syncthreads();
	v_fma_f32 v94, v230, s52, v52
	v_fma_f32 v95, v231, s52, v53
	v_exp_f32_e32 v105, v99
	v_exp_f32_e32 v106, v96
	v_mfma_f32_32x32x16_bf16 a[96:111], v[190:193], v[72:75], a[96:111]
	v_exp_f32_e32 v107, v97
	v_exp_f32_e32 v108, v94
	v_exp_f32_e32 v109, v95
	v_exp_f32_e32 v74, v70
	v_exp_f32_e32 v75, v71
	v_cvt_pk_bf16_f32 v70, v104, v105
	v_cvt_pk_bf16_f32 v71, v106, v107
	v_cvt_pk_bf16_f32 v72, v108, v109
	v_cvt_pk_bf16_f32 v73, v74, v75
	v_add_f32_e32 v68, v90, v68
	v_add_f32_e32 v69, v91, v69
	v_mfma_f32_32x32x16_bf16 a[16:31], v[116:119], v[70:73], a[16:31]
	v_fma_f32 v94, v234, s52, v52
	v_fma_f32 v95, v235, s52, v53
	v_fma_f32 v92, v236, s52, v52
	v_fma_f32 v93, v237, s52, v53
	v_fma_f32 v90, v238, s52, v52
	v_fma_f32 v91, v239, s52, v53
	v_mfma_f32_32x32x16_bf16 a[48:63], v[100:103], v[70:73], a[48:63]
	v_exp_f32_e32 v120, v94
	v_exp_f32_e32 v121, v95
	v_mfma_f32_32x32x16_bf16 a[80:95], v[122:125], v[70:73], a[80:95]
	v_fma_f32 v132, v198, s52, v52
	v_fma_f32 v133, v199, s52, v53
	v_exp_f32_e32 v132, v132
	v_mfma_f32_32x32x16_bf16 a[112:127], v[142:145], v[70:73], a[112:127]
	v_cvt_pk_bf16_f32 v100, v120, v121
	v_exp_f32_e32 v122, v92
	v_exp_f32_e32 v123, v93
	v_exp_f32_e32 v124, v90
	v_exp_f32_e32 v125, v91
	v_cvt_pk_bf16_f32 v101, v122, v123
	v_fma_f32 v70, v240, s52, v52
	v_fma_f32 v71, v241, s52, v53
	v_cvt_pk_bf16_f32 v102, v124, v125
	v_exp_f32_e32 v126, v70
	v_exp_f32_e32 v127, v71
	s_nop 0
	v_cvt_pk_bf16_f32 v103, v126, v127
	v_add_f32_e64 v104, v106, v104
	v_add_f32_e64 v105, v107, v105
	v_mfma_f32_32x32x16_bf16 a[16:31], v[146:149], v[100:103], a[16:31]
	s_andn2_b32 s8, 1, s37
	s_mul_i32 s8, s8, 0x9400
	s_add_i32 s8, s8, 16
	s_waitcnt vmcnt(0)
	v_add3_u32 v54, s8, v77, v76
	ds_write_b128 v54, a[160:163]
	v_add_f32_e32 v104, v108, v104
	v_add_f32_e32 v105, v109, v105
	v_mfma_f32_32x32x16_bf16 a[48:63], v[150:153], v[100:103], a[48:63]
	v_add3_u32 v55, s8, v78, v76
	ds_write_b128 v55, a[144:147] offset:17408
	v_fma_f32 v106, v194, s52, v52
	v_fma_f32 v107, v195, s52, v53
	v_fma_f32 v108, v196, s52, v52
	v_fma_f32 v109, v197, s52, v53
	v_exp_f32_e32 v106, v106
	v_mfma_f32_32x32x16_bf16 a[80:95], v[154:157], v[100:103], a[80:95]
	v_add3_u32 v56, s8, v79, v76
	ds_write_b128 v56, a[164:167]
	v_mfma_f32_32x32x16_bf16 a[112:127], v[158:161], v[100:103], a[112:127]
	v_add3_u32 v57, s8, v80, v76
	ds_write_b128 v57, a[148:151] offset:17408
	v_exp_f32_e32 v107, v107
	v_exp_f32_e32 v108, v108
	v_exp_f32_e32 v109, v109
	v_exp_f32_e32 v133, v133
	v_fma_f32 v100, v200, s52, v52
	v_fma_f32 v101, v201, s52, v53
	v_cvt_pk_bf16_f32 v102, v132, v133
	v_exp_f32_e32 v118, v100
	v_exp_f32_e32 v119, v101
	v_cvt_pk_bf16_f32 v100, v106, v107
	v_cvt_pk_bf16_f32 v101, v108, v109
	v_cvt_pk_bf16_f32 v103, v118, v119
	v_add_f32_e32 v74, v74, v104
	v_add_f32_e32 v75, v75, v105
	v_mfma_f32_32x32x16_bf16 a[16:31], v[162:165], v[100:103], a[16:31]
	v_add3_u32 v58, s8, v81, v76
	ds_write_b128 v58, a[168:171]
	v_add_f32_e32 v104, v122, v120
	v_add_f32_e32 v105, v123, v121
	v_add_f32_e64 v104, v124, v104
	v_add_f32_e64 v105, v125, v105
	v_mfma_f32_32x32x16_bf16 a[48:63], v[166:169], v[100:103], a[48:63]
	v_add3_u32 v59, s8, v82, v76
	ds_write_b128 v59, a[152:155] offset:17408
	v_add_f32_e64 v120, v126, v104
	v_add_f32_e64 v121, v127, v105
	v_mfma_f32_32x32x16_bf16 a[80:95], v[170:173], v[100:103], a[80:95]
	v_add3_u32 v60, s8, v83, v76
	ds_write_b128 v60, a[172:175]
	v_add_f32_e64 v104, v108, v106
	v_mfma_f32_32x32x16_bf16 a[112:127], v[174:177], v[100:103], a[112:127]
	v_add3_u32 v61, s8, v84, v76
	ds_write_b128 v61, a[156:159] offset:17408
	v_add_f32_e64 v105, v109, v107
	v_fma_f32 v112, v206, s52, v52
	v_fma_f32 v113, v207, s52, v53
	v_add_f32_e32 v104, v132, v104
	v_add_f32_e32 v105, v133, v105
	v_exp_f32_e32 v112, v112
	v_exp_f32_e32 v113, v113
	v_fma_f32 v106, v202, s52, v52
	v_fma_f32 v107, v203, s52, v53
	v_exp_f32_e32 v106, v106
	v_exp_f32_e32 v107, v107
	v_fma_f32 v108, v204, s52, v52
	v_fma_f32 v109, v205, s52, v53
	v_add_f32_e64 v114, v118, v104
	v_add_f32_e64 v115, v119, v105
	v_exp_f32_e32 v108, v108
	v_exp_f32_e32 v109, v109
	v_add_f32_e64 v116, v106, 0
	v_add_f32_e64 v117, v107, 0
	v_cvt_pk_bf16_f32 v104, v106, v107
	v_add_f32_e32 v106, v108, v116
	v_add_f32_e32 v107, v109, v117
	v_cvt_pk_bf16_f32 v105, v108, v109
	v_fma_f32 v100, v208, s52, v52
	v_fma_f32 v101, v209, s52, v53
	v_add_f32_e64 v102, v112, v106
	v_add_f32_e64 v103, v113, v107
	v_exp_f32_e32 v100, v100
	v_exp_f32_e32 v101, v101
	v_cvt_pk_bf16_f32 v106, v112, v113
	v_cvt_pk_bf16_f32 v107, v100, v101
	v_add_f32_e64 v100, v100, v102
	v_add_f32_e64 v101, v101, v103
	v_mfma_f32_32x32x16_bf16 a[16:31], v[178:181], v[104:107], a[16:31]
	v_add_f32_e32 v62, v62, v63
	v_add_f32_e32 v74, v74, v75
	v_add_f32_e32 v64, v64, v65
	v_add_f32_e32 v120, v120, v121
	v_add_f32_e32 v66, v66, v67
	v_add_f32_e32 v114, v114, v115
	v_mfma_f32_32x32x16_bf16 a[48:63], v[182:185], v[104:107], a[48:63]
	v_add_f32_e32 v68, v68, v69
	v_add_f32_e32 v100, v100, v101
	v_add_f32_e32 v62, v130, v62
	v_add_f32_e32 v74, v131, v74
	v_add_f32_e32 v62, v64, v62
	v_add_f32_e32 v74, v120, v74
	v_mfma_f32_32x32x16_bf16 a[80:95], v[186:189], v[104:107], a[80:95]
	v_add_f32_e32 v62, v66, v62
	v_add_f32_e32 v74, v114, v74
	v_add_f32_e32 v130, v68, v62
	v_add_f32_e32 v131, v100, v74
	v_mfma_f32_32x32x16_bf16 a[112:127], v[190:193], v[104:107], a[112:127]
	s_branch .Lattn_tail
